# selected-branch tile loop: wave-on test (mask shift, compares) moved above the per-tile barrier
# speedup vs baseline: 1.0050x; 1.0018x over previous
; #define LAS __attribute__((address_space(3)))
; #define MFMA32(a, b, c) __builtin_amdgcn_mfma_f32_32x32x16_bf16((a), (b), (c), 0, 0, 0)
; template <int BR>
; DI void attn_branch(const AttnCtx& c, unsigned long long tmask, const bf16_t* kbase, size_t kpitch, const bf16_t* vbase, size_t vpitch, f32x16 (&o)[2], float& lsum) {
;     ...
;         if (BR == 2) mine = (c.mymask >> jc) & 1ull;
;         const bool wave_on = (BR == 2 ? (__ballot(mine) != 0ull) : true) && !c.nocompute;
;         if (wave_on) {
;             const float sbias = (BR == 2 && !mine) ? -1e30f : 0.f;
;             bool interior;
;             if (BR <= 1) interior = jc * 64 + 64 <= c.ncvmin;
;             else if (BR == 2) interior = jc * 64 + 63 <= c.tw;
;             else interior = (jc * 64 + 63 <= c.tw) && (jc * 64 > c.tw + 31 - 512);
;             if (interior) {
;                 f32x16 s0, s1;
; #pragma unroll
;                 for (int i = 0; i < 16; ++i) { s0[i] = sbias; s1[i] = sbias; }
; #pragma unroll
;                 for (int st = 0; st < 4; ++st) {
;                     const bf16x8 kf0 = *(const LAS bf16x8*)(Ks + c.qi * 72 + 16 * st + 8 * c.hi), kf1 = *(const LAS bf16x8*)(Ks + (32 + c.qi) * 72 + 16 * st + 8 * c.hi);
;                     s0 = MFMA32(kf0, c.q[st], s0); s1 = MFMA32(kf1, c.q[st], s1);
;                 }
;                 float p0[16], p1[16];
; #pragma unroll
;                 for (int i = 0; i < 16; ++i) { p0[i] = __builtin_amdgcn_exp2f(s0[i]); p1[i] = __builtin_amdgcn_exp2f(s1[i]); }
;                 {
;                     float l0 = 0.f, l1 = 0.f;
; #pragma unroll
;                     for (int i = 0; i < 16; ++i) { l0 += p0[i]; l1 += p1[i]; }
;                     lsum += l0 + l1;
;                 }
;                 if (BR == 1) {
; #pragma unroll
;                     for (int gq = 0; gq < 4; ++gq) {
;                         const int jj = jc * 16 + gq * 2 + c.hi;
;                         __hip_atomic_fetch_add(c.impw + jj, (p0[4 * gq] + p0[4 * gq + 1]) + (p0[4 * gq + 2] + p0[4 * gq + 3]), __ATOMIC_RELAXED, __HIP_MEMORY_SCOPE_WORKGROUP);
;                         __hip_atomic_fetch_add(c.impw + jj + 1, p0[4 * gq + 3], __ATOMIC_RELAXED, __HIP_MEMORY_SCOPE_WORKGROUP);
;                     }
; #pragma unroll
;                     for (int gq = 0; gq < 4; ++gq) {
;                         const int jj = jc * 16 + 8 + gq * 2 + c.hi;
.LBB0_377:
	v_lshrrev_b64 v[64:65], s10, v[106:107]
	v_and_b32_e32 v64, 1, v64
	v_cmp_eq_u32_e64 s[0:1], 1, v64
	v_cmp_ne_u32_e32 vcc, 0, v64
	s_waitcnt lgkmcnt(0)
	s_barrier
	s_cbranch_vccz .LBB0_387
	s_lshl_b32 s15, s10, 6
	v_cndmask_b32_e64 v64, v193, 0, s[0:1]
	s_or_b32 s0, s15, 63
	v_cmp_le_i32_e32 vcc, s0, v171
	s_and_saveexec_b64 s[0:1], vcc
	s_xor_b64 s[0:1], exec, s[0:1]
	s_cbranch_execz .LBB0_380
	v_lshlrev_b32_e32 v80, 1, v170
	v_add3_u32 v109, s14, v185, v80
	ds_read_b128 v[212:215], v109
	ds_read_b128 v[216:219], v109 offset:4608
	ds_read_b128 v[220:223], v109 offset:32
	ds_read_b128 v[224:227], v109 offset:4640
	ds_read_b128 v[228:231], v109 offset:64
	ds_read_b128 v[232:235], v109 offset:4672
	ds_read_b128 v[236:239], v109 offset:96
	ds_read_b128 v[240:243], v109 offset:4704
	v_mov_b32_e32 v65, v64
	v_mov_b64_e32 v[66:67], v[64:65]
	v_mov_b64_e32 v[68:69], v[64:65]
	v_mov_b64_e32 v[70:71], v[64:65]
	v_mov_b64_e32 v[72:73], v[64:65]
	v_mov_b64_e32 v[74:75], v[64:65]
	v_mov_b64_e32 v[76:77], v[64:65]
	v_mov_b64_e32 v[78:79], v[64:65]
	s_nop 0
	s_waitcnt lgkmcnt(7)
	v_mfma_f32_32x32x16_bf16 v[80:95], v[212:215], v[130:133], v[64:79]
	s_waitcnt lgkmcnt(5)
	v_mfma_f32_32x32x16_bf16 v[80:95], v[220:223], v[134:137], v[80:95]
	s_waitcnt lgkmcnt(3)
	v_mfma_f32_32x32x16_bf16 v[80:95], v[228:231], v[138:141], v[80:95]
	s_waitcnt lgkmcnt(1)
	v_mfma_f32_32x32x16_bf16 v[80:95], v[236:239], v[142:145], v[80:95]
	s_waitcnt lgkmcnt(0)
	v_mfma_f32_32x32x16_bf16 v[64:79], v[216:219], v[130:133], v[64:79]
	v_mfma_f32_32x32x16_bf16 v[64:79], v[224:227], v[134:137], v[64:79]
	s_nop 9
	v_exp_f32_e32 v80, v80
	v_exp_f32_e32 v81, v81
	v_exp_f32_e32 v82, v82
	v_mfma_f32_32x32x16_bf16 v[64:79], v[232:235], v[138:141], v[64:79]
	v_exp_f32_e32 v83, v83
	v_exp_f32_e32 v84, v84
	v_exp_f32_e32 v85, v85
	v_mfma_f32_32x32x16_bf16 v[64:79], v[240:243], v[142:145], v[64:79]
	v_add3_u32 v251, s14, v186, v170
	v_add_u32_e32 v255, 0x2000, v251
	v_add_u32_e32 v251, 0x3000, v251
	ds_read2_b64 v[212:215], v255 offset0:128 offset1:130
	ds_read2_b64 v[216:219], v251 offset0:160 offset1:162
	ds_read2_b64 v[220:223], v255 offset0:132 offset1:134
	ds_read2_b64 v[224:227], v251 offset0:164 offset1:166
	ds_read2_b64 v[228:231], v255 offset0:136 offset1:138
	ds_read2_b64 v[232:235], v251 offset0:168 offset1:170
	ds_read2_b64 v[236:239], v255 offset0:140 offset1:142
	ds_read2_b64 v[240:243], v251 offset0:172 offset1:174
	v_exp_f32_e32 v86, v86
	v_exp_f32_e32 v87, v87
	v_exp_f32_e32 v88, v88
	v_exp_f32_e32 v89, v89
	v_exp_f32_e32 v90, v90
	v_exp_f32_e32 v91, v91
	v_exp_f32_e32 v92, v92
	v_exp_f32_e32 v93, v93
	v_exp_f32_e32 v94, v94
	v_exp_f32_e32 v95, v95
	v_pk_add_f32 v[252:253], v[80:81], v[82:83]
	v_pk_add_f32 v[254:255], v[84:85], v[86:87]
	v_pk_add_f32 v[252:253], v[88:89], v[252:253]
	v_pk_add_f32 v[254:255], v[90:91], v[254:255]
	v_pk_add_f32 v[252:253], v[92:93], v[252:253]
	v_pk_add_f32 v[254:255], v[94:95], v[254:255]
	v_cvt_pk_bf16_f32 v116, v80, v81
	v_cvt_pk_bf16_f32 v117, v82, v83
	v_cvt_pk_bf16_f32 v118, v84, v85
	v_cvt_pk_bf16_f32 v119, v86, v87
	v_cvt_pk_bf16_f32 v120, v88, v89
	v_cvt_pk_bf16_f32 v121, v90, v91
	v_cvt_pk_bf16_f32 v122, v92, v93
	v_cvt_pk_bf16_f32 v123, v94, v95
	s_waitcnt lgkmcnt(0)
	v_mfma_f32_32x32x16_bf16 v[48:63], v[212:215], v[116:119], v[48:63]
	v_exp_f32_e32 v64, v64
	v_exp_f32_e32 v65, v65
	v_exp_f32_e32 v66, v66
	v_exp_f32_e32 v67, v67
	v_mfma_f32_32x32x16_bf16 v[32:47], v[216:219], v[116:119], v[32:47]
	v_exp_f32_e32 v68, v68
	v_exp_f32_e32 v69, v69
	v_exp_f32_e32 v70, v70
	v_exp_f32_e32 v71, v71
	v_mfma_f32_32x32x16_bf16 v[48:63], v[220:223], v[120:123], v[48:63]
	v_exp_f32_e32 v72, v72
	v_exp_f32_e32 v73, v73
	v_exp_f32_e32 v74, v74
	v_exp_f32_e32 v75, v75
	v_mfma_f32_32x32x16_bf16 v[32:47], v[224:227], v[120:123], v[32:47]
	v_exp_f32_e32 v76, v76
	v_exp_f32_e32 v77, v77
	v_exp_f32_e32 v78, v78
	v_exp_f32_e32 v79, v79
	v_pk_add_f32 v[252:253], v[64:65], v[252:253]
	v_pk_add_f32 v[254:255], v[66:67], v[254:255]
	v_pk_add_f32 v[252:253], v[68:69], v[252:253]
	v_pk_add_f32 v[254:255], v[70:71], v[254:255]
	v_pk_add_f32 v[252:253], v[72:73], v[252:253]
	v_pk_add_f32 v[254:255], v[74:75], v[254:255]
	v_pk_add_f32 v[252:253], v[76:77], v[252:253]
	v_pk_add_f32 v[254:255], v[78:79], v[254:255]
	v_cvt_pk_bf16_f32 v124, v64, v65
	v_cvt_pk_bf16_f32 v125, v66, v67
	v_cvt_pk_bf16_f32 v126, v68, v69
	v_cvt_pk_bf16_f32 v127, v70, v71
	v_pk_add_f32 v[252:253], v[252:253], v[254:255]
	v_cvt_pk_bf16_f32 v80, v72, v73
	v_cvt_pk_bf16_f32 v81, v74, v75
	v_cvt_pk_bf16_f32 v82, v76, v77
	v_cvt_pk_bf16_f32 v83, v78, v79
	v_add_f32_e32 v252, v252, v253
	v_add_f32_e32 v175, v175, v252
	v_mfma_f32_32x32x16_bf16 v[48:63], v[228:231], v[124:127], v[48:63]
	v_mfma_f32_32x32x16_bf16 v[32:47], v[232:235], v[124:127], v[32:47]
	v_mfma_f32_32x32x16_bf16 v[48:63], v[236:239], v[80:83], v[48:63]
	v_mfma_f32_32x32x16_bf16 v[32:47], v[240:243], v[80:83], v[32:47]
